# context-row merge (layer 0): the row's eight loads issued together instead of six dependent load/wait steps, same arithmetic
# speedup vs baseline: 1.0045x; 1.0045x over previous
.LBB0_1088:
	s_cmpk_gt_i32 s16, 0x1ff
	s_mov_b64 s[0:1], -1
	s_cbranch_scc0 .LBB0_1090
	v_mov_b32_e32 v0, v181
	s_lshl_b32 s0, s16, 2
	s_addk_i32 s0, 0x3800
	v_ashrrev_i32_e32 v0, 6, v0
	v_add_u32_e32 v0, s0, v0
	v_mov_b32_e32 v4, v181
	v_ashrrev_i32_e32 v1, 31, v0
	v_lshlrev_b64 v[2:3], 12, v[0:1]
	v_lshlrev_b32_e32 v1, 4, v4
	s_waitcnt lgkmcnt(0)
	v_lshl_add_u64 v[2:3], s[12:13], 0, v[2:3]
	v_and_b32_e32 v164, 0x3f0, v1
	v_lshl_add_u64 v[8:9], v[2:3], 0, v[164:165]
	v_mov_b32_e32 v250, v8
	v_mov_b32_e32 v251, v9
	v_mov_b64_e32 v[252:253], s[14:15]
	v_mad_i64_i32 v[252:253], s[0:1], v0, s49, v[252:253]
	v_lshl_add_u64 v[252:253], v[252:253], 0, v[164:165]
	global_load_dwordx4 v[194:197], v[8:9], off
	global_load_dwordx4 v[198:201], v[8:9], off offset:1024
	global_load_dwordx4 v[242:245], v[8:9], off offset:2048
	global_load_dwordx4 v[246:249], v[8:9], off offset:3072
	global_load_dwordx4 v[202:205], v[252:253], off offset:1664
	global_load_dwordx4 v[206:209], v[252:253], off offset:2688
	global_load_dwordx4 v[210:213], v[252:253], off offset:3712
	s_mov_b64 s[10:11], 0x800
	v_lshl_add_u64 v[252:253], v[252:253], 0, s[10:11]
	global_load_dwordx4 v[214:217], v[252:253], off offset:2688
	s_mov_b32 s0, 0x3a800000
	s_waitcnt vmcnt(0)
	v_lshlrev_b32_e32 v6, 16, v242
	v_lshlrev_b32_e32 v7, 16, v194
	v_and_b32_e32 v8, 0xffff0000, v242
	v_and_b32_e32 v9, 0xffff0000, v194
	v_lshlrev_b32_e32 v10, 16, v243
	v_lshlrev_b32_e32 v11, 16, v195
	v_and_b32_e32 v12, 0xffff0000, v243
	v_and_b32_e32 v13, 0xffff0000, v195
	v_lshlrev_b32_e32 v14, 16, v244
	v_lshlrev_b32_e32 v15, 16, v196
	v_and_b32_e32 v16, 0xffff0000, v244
	v_and_b32_e32 v17, 0xffff0000, v196
	v_lshlrev_b32_e32 v18, 16, v245
	v_lshlrev_b32_e32 v19, 16, v197
	v_and_b32_e32 v20, 0xffff0000, v245
	v_and_b32_e32 v21, 0xffff0000, v197
	v_lshlrev_b32_e32 v22, 16, v246
	v_lshlrev_b32_e32 v23, 16, v198
	v_and_b32_e32 v24, 0xffff0000, v246
	v_and_b32_e32 v25, 0xffff0000, v198
	v_lshlrev_b32_e32 v26, 16, v247
	v_lshlrev_b32_e32 v27, 16, v199
	v_and_b32_e32 v28, 0xffff0000, v247
	v_and_b32_e32 v29, 0xffff0000, v199
	v_lshlrev_b32_e32 v30, 16, v248
	v_lshlrev_b32_e32 v31, 16, v200
	v_and_b32_e32 v32, 0xffff0000, v248
	v_and_b32_e32 v33, 0xffff0000, v200
	v_lshlrev_b32_e32 v34, 16, v249
	v_lshlrev_b32_e32 v35, 16, v201
	v_and_b32_e32 v36, 0xffff0000, v249
	v_and_b32_e32 v37, 0xffff0000, v201
	v_pk_mul_f32 v[38:39], v[8:9], v[8:9]
	v_pk_fma_f32 v[38:39], v[6:7], v[6:7], v[38:39]
	v_pk_fma_f32 v[38:39], v[10:11], v[10:11], v[38:39]
	v_pk_fma_f32 v[38:39], v[12:13], v[12:13], v[38:39]
	v_pk_fma_f32 v[38:39], v[14:15], v[14:15], v[38:39]
	v_pk_fma_f32 v[38:39], v[16:17], v[16:17], v[38:39]
	v_pk_fma_f32 v[38:39], v[18:19], v[18:19], v[38:39]
	v_pk_fma_f32 v[38:39], v[20:21], v[20:21], v[38:39]
	v_pk_fma_f32 v[38:39], v[22:23], v[22:23], v[38:39]
	v_pk_fma_f32 v[38:39], v[24:25], v[24:25], v[38:39]
	v_pk_fma_f32 v[38:39], v[26:27], v[26:27], v[38:39]
	v_pk_fma_f32 v[38:39], v[28:29], v[28:29], v[38:39]
	v_pk_mul_f32 v[48:49], v[30:31], v[30:31]
	v_pk_add_f32 v[38:39], v[48:49], v[38:39]
	v_pk_mul_f32 v[48:49], v[32:33], v[32:33]
	v_pk_add_f32 v[38:39], v[48:49], v[38:39]
	v_pk_mul_f32 v[48:49], v[34:35], v[34:35]
	v_pk_add_f32 v[38:39], v[48:49], v[38:39]
	v_pk_mul_f32 v[48:49], v[36:37], v[36:37]
	v_pk_add_f32 v[38:39], v[48:49], v[38:39]
	v_mov_b32_e32 v48, v38
	v_mov_b32_e32 v49, v39
	s_nop 1
	v_permlane32_swap_b32_e32 v38, v48
	v_permlane32_swap_b32_e32 v39, v49
	s_nop 0
	v_add_f32_e32 v38, v38, v48
	v_add_f32_e32 v39, v39, v49
	v_mov_b32_e32 v48, v38
	v_mov_b32_e32 v49, v39
	s_nop 1
	v_permlane16_swap_b32_e32 v38, v48
	v_permlane16_swap_b32_e32 v39, v49
	s_nop 0
	v_add_f32_e32 v38, v38, v48
	v_add_f32_e32 v39, v39, v49
	s_nop 1
	v_add_f32_dpp v38, v38, v38 row_ror:8 row_mask:0xf bank_mask:0xf
	v_add_f32_dpp v39, v39, v39 row_ror:8 row_mask:0xf bank_mask:0xf
	s_nop 1
	v_add_f32_dpp v38, v38, v38 row_ror:4 row_mask:0xf bank_mask:0xf
	v_add_f32_dpp v39, v39, v39 row_ror:4 row_mask:0xf bank_mask:0xf
	s_nop 1
	v_add_f32_dpp v38, v38, v38 row_ror:2 row_mask:0xf bank_mask:0xf
	v_add_f32_dpp v39, v39, v39 row_ror:2 row_mask:0xf bank_mask:0xf
	s_nop 1
	v_add_f32_dpp v38, v38, v38 row_ror:1 row_mask:0xf bank_mask:0xf
	v_add_f32_dpp v39, v39, v39 row_ror:1 row_mask:0xf bank_mask:0xf
	s_nop 1
	v_pk_fma_f32 v[38:39], v[38:39], s[0:1], v[166:167] op_sel_hi:[1,0,0]
	s_nop 0
	v_mul_f32_e32 v47, 0x4b800000, v39
	v_cmp_gt_f32_e64 s[10:11], s58, v39
	v_cmp_gt_f32_e32 vcc, s58, v38
	s_nop 1
	v_cndmask_b32_e64 v39, v39, v47, s[10:11]
	v_rsq_f32_e32 v39, v39
	s_nop 0
	v_mul_f32_e32 v47, 0x45800000, v39
	v_cndmask_b32_e64 v57, v39, v47, s[10:11]
	v_mul_f32_e32 v39, 0x4b800000, v38
	v_cndmask_b32_e32 v38, v38, v39, vcc
	v_rsq_f32_e32 v38, v38
	s_nop 0
	v_mul_f32_e32 v39, 0x45800000, v38
	v_cndmask_b32_e32 v58, v38, v39, vcc
	v_mul_f32_e32 v6, v58, v6
	v_mul_f32_e32 v7, v57, v7
	v_mul_f32_e32 v8, v58, v8
	v_mul_f32_e32 v9, v57, v9
	v_mul_f32_e32 v10, v58, v10
	v_mul_f32_e32 v11, v57, v11
	v_mul_f32_e32 v12, v58, v12
	v_mul_f32_e32 v13, v57, v13
	v_mul_f32_e32 v14, v58, v14
	v_mul_f32_e32 v15, v57, v15
	v_mul_f32_e32 v16, v58, v16
	v_mul_f32_e32 v17, v57, v17
	v_mul_f32_e32 v18, v58, v18
	v_mul_f32_e32 v19, v57, v19
	v_mul_f32_e32 v20, v58, v20
	v_mul_f32_e32 v21, v57, v21
	v_mul_f32_e32 v22, v58, v22
	v_mul_f32_e32 v23, v57, v23
	v_mul_f32_e32 v24, v58, v24
	v_mul_f32_e32 v25, v57, v25
	v_mul_f32_e32 v26, v58, v26
	v_mul_f32_e32 v27, v57, v27
	v_mul_f32_e32 v28, v58, v28
	v_mul_f32_e32 v29, v57, v29
	v_mul_f32_e32 v30, v58, v30
	v_mul_f32_e32 v31, v57, v31
	v_mul_f32_e32 v32, v58, v32
	v_mul_f32_e32 v33, v57, v33
	v_mul_f32_e32 v34, v58, v34
	v_mul_f32_e32 v35, v57, v35
	v_mul_f32_e32 v36, v58, v36
	v_mul_f32_e32 v37, v57, v37
	v_lshlrev_b32_e32 v40, 16, v202
	v_and_b32_e32 v50, 0xffff0000, v202
	v_mul_f32_e32 v41, 0xbfb8aa3b, v40
	v_mul_f32_e32 v51, 0xbfb8aa3b, v50
	v_exp_f32_e32 v41, v41
	v_exp_f32_e32 v51, v51
	v_add_f32_e32 v41, 1.0, v41
	v_add_f32_e32 v51, 1.0, v51
	v_div_scale_f32 v42, s[8:9], v41, v41, v40
	v_div_scale_f32 v52, s[8:9], v51, v51, v50
	v_rcp_f32_e32 v43, v42
	v_rcp_f32_e32 v53, v52
	v_fma_f32 v44, -v42, v43, 1.0
	v_fma_f32 v54, -v52, v53, 1.0
	v_fmac_f32_e32 v43, v44, v43
	v_fmac_f32_e32 v53, v54, v53
	v_div_scale_f32 v45, vcc, v40, v41, v40
	v_mul_f32_e32 v46, v45, v43
	v_fma_f32 v44, -v42, v46, v45
	v_fmac_f32_e32 v46, v44, v43
	v_fma_f32 v42, -v42, v46, v45
	v_div_fmas_f32 v42, v42, v43, v46
	v_div_fixup_f32 v42, v42, v41, v40
	v_mul_f32_e32 v7, v7, v42
	v_div_scale_f32 v55, vcc, v50, v51, v50
	v_mul_f32_e32 v56, v55, v53
	v_fma_f32 v54, -v52, v56, v55
	v_fmac_f32_e32 v56, v54, v53
	v_fma_f32 v52, -v52, v56, v55
	v_div_fmas_f32 v52, v52, v53, v56
	v_div_fixup_f32 v52, v52, v51, v50
	v_mul_f32_e32 v9, v9, v52
	v_cvt_pk_bf16_f32 v194, v7, v9
	v_lshlrev_b32_e32 v40, 16, v203
	v_and_b32_e32 v50, 0xffff0000, v203
	v_mul_f32_e32 v41, 0xbfb8aa3b, v40
	v_mul_f32_e32 v51, 0xbfb8aa3b, v50
	v_exp_f32_e32 v41, v41
	v_exp_f32_e32 v51, v51
	v_add_f32_e32 v41, 1.0, v41
	v_add_f32_e32 v51, 1.0, v51
	v_div_scale_f32 v42, s[8:9], v41, v41, v40
	v_div_scale_f32 v52, s[8:9], v51, v51, v50
	v_rcp_f32_e32 v43, v42
	v_rcp_f32_e32 v53, v52
	v_fma_f32 v44, -v42, v43, 1.0
	v_fma_f32 v54, -v52, v53, 1.0
	v_fmac_f32_e32 v43, v44, v43
	v_fmac_f32_e32 v53, v54, v53
	v_div_scale_f32 v45, vcc, v40, v41, v40
	v_mul_f32_e32 v46, v45, v43
	v_fma_f32 v44, -v42, v46, v45
	v_fmac_f32_e32 v46, v44, v43
	v_fma_f32 v42, -v42, v46, v45
	v_div_fmas_f32 v42, v42, v43, v46
	v_div_fixup_f32 v42, v42, v41, v40
	v_mul_f32_e32 v11, v11, v42
	v_div_scale_f32 v55, vcc, v50, v51, v50
	v_mul_f32_e32 v56, v55, v53
	v_fma_f32 v54, -v52, v56, v55
	v_fmac_f32_e32 v56, v54, v53
	v_fma_f32 v52, -v52, v56, v55
	v_div_fmas_f32 v52, v52, v53, v56
	v_div_fixup_f32 v52, v52, v51, v50
	v_mul_f32_e32 v13, v13, v52
	v_cvt_pk_bf16_f32 v195, v11, v13
	v_lshlrev_b32_e32 v40, 16, v204
	v_and_b32_e32 v50, 0xffff0000, v204
	v_mul_f32_e32 v41, 0xbfb8aa3b, v40
	v_mul_f32_e32 v51, 0xbfb8aa3b, v50
	v_exp_f32_e32 v41, v41
	v_exp_f32_e32 v51, v51
	v_add_f32_e32 v41, 1.0, v41
	v_add_f32_e32 v51, 1.0, v51
	v_div_scale_f32 v42, s[8:9], v41, v41, v40
	v_div_scale_f32 v52, s[8:9], v51, v51, v50
	v_rcp_f32_e32 v43, v42
	v_rcp_f32_e32 v53, v52
	v_fma_f32 v44, -v42, v43, 1.0
	v_fma_f32 v54, -v52, v53, 1.0
	v_fmac_f32_e32 v43, v44, v43
	v_fmac_f32_e32 v53, v54, v53
	v_div_scale_f32 v45, vcc, v40, v41, v40
	v_mul_f32_e32 v46, v45, v43
	v_fma_f32 v44, -v42, v46, v45
	v_fmac_f32_e32 v46, v44, v43
	v_fma_f32 v42, -v42, v46, v45
	v_div_fmas_f32 v42, v42, v43, v46
	v_div_fixup_f32 v42, v42, v41, v40
	v_mul_f32_e32 v15, v15, v42
	v_div_scale_f32 v55, vcc, v50, v51, v50
	v_mul_f32_e32 v56, v55, v53
	v_fma_f32 v54, -v52, v56, v55
	v_fmac_f32_e32 v56, v54, v53
	v_fma_f32 v52, -v52, v56, v55
	v_div_fmas_f32 v52, v52, v53, v56
	v_div_fixup_f32 v52, v52, v51, v50
	v_mul_f32_e32 v17, v17, v52
	v_cvt_pk_bf16_f32 v196, v15, v17
	v_lshlrev_b32_e32 v40, 16, v205
	v_and_b32_e32 v50, 0xffff0000, v205
	v_mul_f32_e32 v41, 0xbfb8aa3b, v40
	v_mul_f32_e32 v51, 0xbfb8aa3b, v50
	v_exp_f32_e32 v41, v41
	v_exp_f32_e32 v51, v51
	v_add_f32_e32 v41, 1.0, v41
	v_add_f32_e32 v51, 1.0, v51
	v_div_scale_f32 v42, s[8:9], v41, v41, v40
	v_div_scale_f32 v52, s[8:9], v51, v51, v50
	v_rcp_f32_e32 v43, v42
	v_rcp_f32_e32 v53, v52
	v_fma_f32 v44, -v42, v43, 1.0
	v_fma_f32 v54, -v52, v53, 1.0
	v_fmac_f32_e32 v43, v44, v43
	v_fmac_f32_e32 v53, v54, v53
	v_div_scale_f32 v45, vcc, v40, v41, v40
	v_mul_f32_e32 v46, v45, v43
	v_fma_f32 v44, -v42, v46, v45
	v_fmac_f32_e32 v46, v44, v43
	v_fma_f32 v42, -v42, v46, v45
	v_div_fmas_f32 v42, v42, v43, v46
	v_div_fixup_f32 v42, v42, v41, v40
	v_mul_f32_e32 v19, v19, v42
	v_div_scale_f32 v55, vcc, v50, v51, v50
	v_mul_f32_e32 v56, v55, v53
	v_fma_f32 v54, -v52, v56, v55
	v_fmac_f32_e32 v56, v54, v53
	v_fma_f32 v52, -v52, v56, v55
	v_div_fmas_f32 v52, v52, v53, v56
	v_div_fixup_f32 v52, v52, v51, v50
	v_mul_f32_e32 v21, v21, v52
	v_cvt_pk_bf16_f32 v197, v19, v21
	v_lshlrev_b32_e32 v40, 16, v210
	v_and_b32_e32 v50, 0xffff0000, v210
	v_mul_f32_e32 v41, 0xbfb8aa3b, v40
	v_mul_f32_e32 v51, 0xbfb8aa3b, v50
	v_exp_f32_e32 v41, v41
	v_exp_f32_e32 v51, v51
	v_add_f32_e32 v41, 1.0, v41
	v_add_f32_e32 v51, 1.0, v51
	v_div_scale_f32 v42, s[8:9], v41, v41, v40
	v_div_scale_f32 v52, s[8:9], v51, v51, v50
	v_rcp_f32_e32 v43, v42
	v_rcp_f32_e32 v53, v52
	v_fma_f32 v44, -v42, v43, 1.0
	v_fma_f32 v54, -v52, v53, 1.0
	v_fmac_f32_e32 v43, v44, v43
	v_fmac_f32_e32 v53, v54, v53
	v_div_scale_f32 v45, vcc, v40, v41, v40
	v_mul_f32_e32 v46, v45, v43
	v_fma_f32 v44, -v42, v46, v45
	v_fmac_f32_e32 v46, v44, v43
	v_fma_f32 v42, -v42, v46, v45
	v_div_fmas_f32 v42, v42, v43, v46
	v_div_fixup_f32 v42, v42, v41, v40
	v_mul_f32_e32 v6, v6, v42
	v_div_scale_f32 v55, vcc, v50, v51, v50
	v_mul_f32_e32 v56, v55, v53
	v_fma_f32 v54, -v52, v56, v55
	v_fmac_f32_e32 v56, v54, v53
	v_fma_f32 v52, -v52, v56, v55
	v_div_fmas_f32 v52, v52, v53, v56
	v_div_fixup_f32 v52, v52, v51, v50
	v_mul_f32_e32 v8, v8, v52
	v_cvt_pk_bf16_f32 v202, v6, v8
	v_lshlrev_b32_e32 v40, 16, v211
	v_and_b32_e32 v50, 0xffff0000, v211
	v_mul_f32_e32 v41, 0xbfb8aa3b, v40
	v_mul_f32_e32 v51, 0xbfb8aa3b, v50
	v_exp_f32_e32 v41, v41
	v_exp_f32_e32 v51, v51
	v_add_f32_e32 v41, 1.0, v41
	v_add_f32_e32 v51, 1.0, v51
	v_div_scale_f32 v42, s[8:9], v41, v41, v40
	v_div_scale_f32 v52, s[8:9], v51, v51, v50
	v_rcp_f32_e32 v43, v42
	v_rcp_f32_e32 v53, v52
	v_fma_f32 v44, -v42, v43, 1.0
	v_fma_f32 v54, -v52, v53, 1.0
	v_fmac_f32_e32 v43, v44, v43
	v_fmac_f32_e32 v53, v54, v53
	v_div_scale_f32 v45, vcc, v40, v41, v40
	v_mul_f32_e32 v46, v45, v43
	v_fma_f32 v44, -v42, v46, v45
	v_fmac_f32_e32 v46, v44, v43
	v_fma_f32 v42, -v42, v46, v45
	v_div_fmas_f32 v42, v42, v43, v46
	v_div_fixup_f32 v42, v42, v41, v40
	v_mul_f32_e32 v10, v10, v42
	v_div_scale_f32 v55, vcc, v50, v51, v50
	v_mul_f32_e32 v56, v55, v53
	v_fma_f32 v54, -v52, v56, v55
	v_fmac_f32_e32 v56, v54, v53
	v_fma_f32 v52, -v52, v56, v55
	v_div_fmas_f32 v52, v52, v53, v56
	v_div_fixup_f32 v52, v52, v51, v50
	v_mul_f32_e32 v12, v12, v52
	v_cvt_pk_bf16_f32 v203, v10, v12
	v_lshlrev_b32_e32 v40, 16, v212
	v_and_b32_e32 v50, 0xffff0000, v212
	v_mul_f32_e32 v41, 0xbfb8aa3b, v40
	v_mul_f32_e32 v51, 0xbfb8aa3b, v50
	v_exp_f32_e32 v41, v41
	v_exp_f32_e32 v51, v51
	v_add_f32_e32 v41, 1.0, v41
	v_add_f32_e32 v51, 1.0, v51
	v_div_scale_f32 v42, s[8:9], v41, v41, v40
	v_div_scale_f32 v52, s[8:9], v51, v51, v50
	v_rcp_f32_e32 v43, v42
	v_rcp_f32_e32 v53, v52
	v_fma_f32 v44, -v42, v43, 1.0
	v_fma_f32 v54, -v52, v53, 1.0
	v_fmac_f32_e32 v43, v44, v43
	v_fmac_f32_e32 v53, v54, v53
	v_div_scale_f32 v45, vcc, v40, v41, v40
	v_mul_f32_e32 v46, v45, v43
	v_fma_f32 v44, -v42, v46, v45
	v_fmac_f32_e32 v46, v44, v43
	v_fma_f32 v42, -v42, v46, v45
	v_div_fmas_f32 v42, v42, v43, v46
	v_div_fixup_f32 v42, v42, v41, v40
	v_mul_f32_e32 v14, v14, v42
	v_div_scale_f32 v55, vcc, v50, v51, v50
	v_mul_f32_e32 v56, v55, v53
	v_fma_f32 v54, -v52, v56, v55
	v_fmac_f32_e32 v56, v54, v53
	v_fma_f32 v52, -v52, v56, v55
	v_div_fmas_f32 v52, v52, v53, v56
	v_div_fixup_f32 v52, v52, v51, v50
	v_mul_f32_e32 v16, v16, v52
	v_cvt_pk_bf16_f32 v204, v14, v16
	v_lshlrev_b32_e32 v40, 16, v213
	v_and_b32_e32 v50, 0xffff0000, v213
	v_mul_f32_e32 v41, 0xbfb8aa3b, v40
	v_mul_f32_e32 v51, 0xbfb8aa3b, v50
	v_exp_f32_e32 v41, v41
	v_exp_f32_e32 v51, v51
	v_add_f32_e32 v41, 1.0, v41
	v_add_f32_e32 v51, 1.0, v51
	v_div_scale_f32 v42, s[8:9], v41, v41, v40
	v_div_scale_f32 v52, s[8:9], v51, v51, v50
	v_rcp_f32_e32 v43, v42
	v_rcp_f32_e32 v53, v52
	v_fma_f32 v44, -v42, v43, 1.0
	v_fma_f32 v54, -v52, v53, 1.0
	v_fmac_f32_e32 v43, v44, v43
	v_fmac_f32_e32 v53, v54, v53
	v_div_scale_f32 v45, vcc, v40, v41, v40
	v_mul_f32_e32 v46, v45, v43
	v_fma_f32 v44, -v42, v46, v45
	v_fmac_f32_e32 v46, v44, v43
	v_fma_f32 v42, -v42, v46, v45
	v_div_fmas_f32 v42, v42, v43, v46
	v_div_fixup_f32 v42, v42, v41, v40
	v_mul_f32_e32 v18, v18, v42
	v_div_scale_f32 v55, vcc, v50, v51, v50
	v_mul_f32_e32 v56, v55, v53
	v_fma_f32 v54, -v52, v56, v55
	v_fmac_f32_e32 v56, v54, v53
	v_fma_f32 v52, -v52, v56, v55
	v_div_fmas_f32 v52, v52, v53, v56
	v_div_fixup_f32 v52, v52, v51, v50
	v_mul_f32_e32 v20, v20, v52
	v_cvt_pk_bf16_f32 v205, v18, v20
	global_store_dwordx4 v[250:251], v[194:197], off
	global_store_dwordx4 v[250:251], v[202:205], off offset:2048
	v_lshlrev_b32_e32 v40, 16, v206
	v_and_b32_e32 v50, 0xffff0000, v206
	v_mul_f32_e32 v41, 0xbfb8aa3b, v40
	v_mul_f32_e32 v51, 0xbfb8aa3b, v50
	v_exp_f32_e32 v41, v41
	v_exp_f32_e32 v51, v51
	v_add_f32_e32 v41, 1.0, v41
	v_add_f32_e32 v51, 1.0, v51
	v_div_scale_f32 v42, s[8:9], v41, v41, v40
	v_div_scale_f32 v52, s[8:9], v51, v51, v50
	v_rcp_f32_e32 v43, v42
	v_rcp_f32_e32 v53, v52
	v_fma_f32 v44, -v42, v43, 1.0
	v_fma_f32 v54, -v52, v53, 1.0
	v_fmac_f32_e32 v43, v44, v43
	v_fmac_f32_e32 v53, v54, v53
	v_div_scale_f32 v45, vcc, v40, v41, v40
	v_mul_f32_e32 v46, v45, v43
	v_fma_f32 v44, -v42, v46, v45
	v_fmac_f32_e32 v46, v44, v43
	v_fma_f32 v42, -v42, v46, v45
	v_div_fmas_f32 v42, v42, v43, v46
	v_div_fixup_f32 v42, v42, v41, v40
	v_mul_f32_e32 v23, v23, v42
	v_div_scale_f32 v55, vcc, v50, v51, v50
	v_mul_f32_e32 v56, v55, v53
	v_fma_f32 v54, -v52, v56, v55
	v_fmac_f32_e32 v56, v54, v53
	v_fma_f32 v52, -v52, v56, v55
	v_div_fmas_f32 v52, v52, v53, v56
	v_div_fixup_f32 v52, v52, v51, v50
	v_mul_f32_e32 v25, v25, v52
	v_cvt_pk_bf16_f32 v198, v23, v25
	v_lshlrev_b32_e32 v40, 16, v207
	v_and_b32_e32 v50, 0xffff0000, v207
	v_mul_f32_e32 v41, 0xbfb8aa3b, v40
	v_mul_f32_e32 v51, 0xbfb8aa3b, v50
	v_exp_f32_e32 v41, v41
	v_exp_f32_e32 v51, v51
	v_add_f32_e32 v41, 1.0, v41
	v_add_f32_e32 v51, 1.0, v51
	v_div_scale_f32 v42, s[8:9], v41, v41, v40
	v_div_scale_f32 v52, s[8:9], v51, v51, v50
	v_rcp_f32_e32 v43, v42
	v_rcp_f32_e32 v53, v52
	v_fma_f32 v44, -v42, v43, 1.0
	v_fma_f32 v54, -v52, v53, 1.0
	v_fmac_f32_e32 v43, v44, v43
	v_fmac_f32_e32 v53, v54, v53
	v_div_scale_f32 v45, vcc, v40, v41, v40
	v_mul_f32_e32 v46, v45, v43
	v_fma_f32 v44, -v42, v46, v45
	v_fmac_f32_e32 v46, v44, v43
	v_fma_f32 v42, -v42, v46, v45
	v_div_fmas_f32 v42, v42, v43, v46
	v_div_fixup_f32 v42, v42, v41, v40
	v_mul_f32_e32 v27, v27, v42
	v_div_scale_f32 v55, vcc, v50, v51, v50
	v_mul_f32_e32 v56, v55, v53
	v_fma_f32 v54, -v52, v56, v55
	v_fmac_f32_e32 v56, v54, v53
	v_fma_f32 v52, -v52, v56, v55
	v_div_fmas_f32 v52, v52, v53, v56
	v_div_fixup_f32 v52, v52, v51, v50
	v_mul_f32_e32 v29, v29, v52
	v_cvt_pk_bf16_f32 v199, v27, v29
	v_lshlrev_b32_e32 v40, 16, v208
	v_and_b32_e32 v50, 0xffff0000, v208
	v_mul_f32_e32 v41, 0xbfb8aa3b, v40
	v_mul_f32_e32 v51, 0xbfb8aa3b, v50
	v_exp_f32_e32 v41, v41
	v_exp_f32_e32 v51, v51
	v_add_f32_e32 v41, 1.0, v41
	v_add_f32_e32 v51, 1.0, v51
	v_div_scale_f32 v42, s[8:9], v41, v41, v40
	v_div_scale_f32 v52, s[8:9], v51, v51, v50
	v_rcp_f32_e32 v43, v42
	v_rcp_f32_e32 v53, v52
	v_fma_f32 v44, -v42, v43, 1.0
	v_fma_f32 v54, -v52, v53, 1.0
	v_fmac_f32_e32 v43, v44, v43
	v_fmac_f32_e32 v53, v54, v53
	v_div_scale_f32 v45, vcc, v40, v41, v40
	v_mul_f32_e32 v46, v45, v43
	v_fma_f32 v44, -v42, v46, v45
	v_fmac_f32_e32 v46, v44, v43
	v_fma_f32 v42, -v42, v46, v45
	v_div_fmas_f32 v42, v42, v43, v46
	v_div_fixup_f32 v42, v42, v41, v40
	v_mul_f32_e32 v31, v31, v42
	v_div_scale_f32 v55, vcc, v50, v51, v50
	v_mul_f32_e32 v56, v55, v53
	v_fma_f32 v54, -v52, v56, v55
	v_fmac_f32_e32 v56, v54, v53
	v_fma_f32 v52, -v52, v56, v55
	v_div_fmas_f32 v52, v52, v53, v56
	v_div_fixup_f32 v52, v52, v51, v50
	v_mul_f32_e32 v33, v33, v52
	v_cvt_pk_bf16_f32 v200, v31, v33
	v_lshlrev_b32_e32 v40, 16, v209
	v_and_b32_e32 v50, 0xffff0000, v209
	v_mul_f32_e32 v41, 0xbfb8aa3b, v40
	v_mul_f32_e32 v51, 0xbfb8aa3b, v50
	v_exp_f32_e32 v41, v41
	v_exp_f32_e32 v51, v51
	v_add_f32_e32 v41, 1.0, v41
	v_add_f32_e32 v51, 1.0, v51
	v_div_scale_f32 v42, s[8:9], v41, v41, v40
	v_div_scale_f32 v52, s[8:9], v51, v51, v50
	v_rcp_f32_e32 v43, v42
	v_rcp_f32_e32 v53, v52
	v_fma_f32 v44, -v42, v43, 1.0
	v_fma_f32 v54, -v52, v53, 1.0
	v_fmac_f32_e32 v43, v44, v43
	v_fmac_f32_e32 v53, v54, v53
	v_div_scale_f32 v45, vcc, v40, v41, v40
	v_mul_f32_e32 v46, v45, v43
	v_fma_f32 v44, -v42, v46, v45
	v_fmac_f32_e32 v46, v44, v43
	v_fma_f32 v42, -v42, v46, v45
	v_div_fmas_f32 v42, v42, v43, v46
	v_div_fixup_f32 v42, v42, v41, v40
	v_mul_f32_e32 v35, v35, v42
	v_div_scale_f32 v55, vcc, v50, v51, v50
	v_mul_f32_e32 v56, v55, v53
	v_fma_f32 v54, -v52, v56, v55
	v_fmac_f32_e32 v56, v54, v53
	v_fma_f32 v52, -v52, v56, v55
	v_div_fmas_f32 v52, v52, v53, v56
	v_div_fixup_f32 v52, v52, v51, v50
	v_mul_f32_e32 v37, v37, v52
	v_cvt_pk_bf16_f32 v201, v35, v37
	v_lshlrev_b32_e32 v40, 16, v214
	v_and_b32_e32 v50, 0xffff0000, v214
	v_mul_f32_e32 v41, 0xbfb8aa3b, v40
	v_mul_f32_e32 v51, 0xbfb8aa3b, v50
	v_exp_f32_e32 v41, v41
	v_exp_f32_e32 v51, v51
	v_add_f32_e32 v41, 1.0, v41
	v_add_f32_e32 v51, 1.0, v51
	v_div_scale_f32 v42, s[8:9], v41, v41, v40
	v_div_scale_f32 v52, s[8:9], v51, v51, v50
	v_rcp_f32_e32 v43, v42
	v_rcp_f32_e32 v53, v52
	v_fma_f32 v44, -v42, v43, 1.0
	v_fma_f32 v54, -v52, v53, 1.0
	v_fmac_f32_e32 v43, v44, v43
	v_fmac_f32_e32 v53, v54, v53
	v_div_scale_f32 v45, vcc, v40, v41, v40
	v_mul_f32_e32 v46, v45, v43
	v_fma_f32 v44, -v42, v46, v45
	v_fmac_f32_e32 v46, v44, v43
	v_fma_f32 v42, -v42, v46, v45
	v_div_fmas_f32 v42, v42, v43, v46
	v_div_fixup_f32 v42, v42, v41, v40
	v_mul_f32_e32 v22, v22, v42
	v_div_scale_f32 v55, vcc, v50, v51, v50
	v_mul_f32_e32 v56, v55, v53
	v_fma_f32 v54, -v52, v56, v55
	v_fmac_f32_e32 v56, v54, v53
	v_fma_f32 v52, -v52, v56, v55
	v_div_fmas_f32 v52, v52, v53, v56
	v_div_fixup_f32 v52, v52, v51, v50
	v_mul_f32_e32 v24, v24, v52
	v_cvt_pk_bf16_f32 v206, v22, v24
	v_lshlrev_b32_e32 v40, 16, v215
	v_and_b32_e32 v50, 0xffff0000, v215
	v_mul_f32_e32 v41, 0xbfb8aa3b, v40
	v_mul_f32_e32 v51, 0xbfb8aa3b, v50
	v_exp_f32_e32 v41, v41
	v_exp_f32_e32 v51, v51
	v_add_f32_e32 v41, 1.0, v41
	v_add_f32_e32 v51, 1.0, v51
	v_div_scale_f32 v42, s[8:9], v41, v41, v40
	v_div_scale_f32 v52, s[8:9], v51, v51, v50
	v_rcp_f32_e32 v43, v42
	v_rcp_f32_e32 v53, v52
	v_fma_f32 v44, -v42, v43, 1.0
	v_fma_f32 v54, -v52, v53, 1.0
	v_fmac_f32_e32 v43, v44, v43
	v_fmac_f32_e32 v53, v54, v53
	v_div_scale_f32 v45, vcc, v40, v41, v40
	v_mul_f32_e32 v46, v45, v43
	v_fma_f32 v44, -v42, v46, v45
	v_fmac_f32_e32 v46, v44, v43
	v_fma_f32 v42, -v42, v46, v45
	v_div_fmas_f32 v42, v42, v43, v46
	v_div_fixup_f32 v42, v42, v41, v40
	v_mul_f32_e32 v26, v26, v42
	v_div_scale_f32 v55, vcc, v50, v51, v50
	v_mul_f32_e32 v56, v55, v53
	v_fma_f32 v54, -v52, v56, v55
	v_fmac_f32_e32 v56, v54, v53
	v_fma_f32 v52, -v52, v56, v55
	v_div_fmas_f32 v52, v52, v53, v56
	v_div_fixup_f32 v52, v52, v51, v50
	v_mul_f32_e32 v28, v28, v52
	v_cvt_pk_bf16_f32 v207, v26, v28
	v_lshlrev_b32_e32 v40, 16, v216
	v_and_b32_e32 v50, 0xffff0000, v216
	v_mul_f32_e32 v41, 0xbfb8aa3b, v40
	v_mul_f32_e32 v51, 0xbfb8aa3b, v50
	v_exp_f32_e32 v41, v41
	v_exp_f32_e32 v51, v51
	v_add_f32_e32 v41, 1.0, v41
	v_add_f32_e32 v51, 1.0, v51
	v_div_scale_f32 v42, s[8:9], v41, v41, v40
	v_div_scale_f32 v52, s[8:9], v51, v51, v50
	v_rcp_f32_e32 v43, v42
	v_rcp_f32_e32 v53, v52
	v_fma_f32 v44, -v42, v43, 1.0
	v_fma_f32 v54, -v52, v53, 1.0
	v_fmac_f32_e32 v43, v44, v43
	v_fmac_f32_e32 v53, v54, v53
	v_div_scale_f32 v45, vcc, v40, v41, v40
	v_mul_f32_e32 v46, v45, v43
	v_fma_f32 v44, -v42, v46, v45
	v_fmac_f32_e32 v46, v44, v43
	v_fma_f32 v42, -v42, v46, v45
	v_div_fmas_f32 v42, v42, v43, v46
	v_div_fixup_f32 v42, v42, v41, v40
	v_mul_f32_e32 v30, v30, v42
	v_div_scale_f32 v55, vcc, v50, v51, v50
	v_mul_f32_e32 v56, v55, v53
	v_fma_f32 v54, -v52, v56, v55
	v_fmac_f32_e32 v56, v54, v53
	v_fma_f32 v52, -v52, v56, v55
	v_div_fmas_f32 v52, v52, v53, v56
	v_div_fixup_f32 v52, v52, v51, v50
	v_mul_f32_e32 v32, v32, v52
	v_cvt_pk_bf16_f32 v208, v30, v32
	v_lshlrev_b32_e32 v40, 16, v217
	v_and_b32_e32 v50, 0xffff0000, v217
	v_mul_f32_e32 v41, 0xbfb8aa3b, v40
	v_mul_f32_e32 v51, 0xbfb8aa3b, v50
	v_exp_f32_e32 v41, v41
	v_exp_f32_e32 v51, v51
	v_add_f32_e32 v41, 1.0, v41
	v_add_f32_e32 v51, 1.0, v51
	v_div_scale_f32 v42, s[8:9], v41, v41, v40
	v_div_scale_f32 v52, s[8:9], v51, v51, v50
	v_rcp_f32_e32 v43, v42
	v_rcp_f32_e32 v53, v52
	v_fma_f32 v44, -v42, v43, 1.0
	v_fma_f32 v54, -v52, v53, 1.0
	v_fmac_f32_e32 v43, v44, v43
	v_fmac_f32_e32 v53, v54, v53
	v_div_scale_f32 v45, vcc, v40, v41, v40
	v_mul_f32_e32 v46, v45, v43
	v_fma_f32 v44, -v42, v46, v45
	v_fmac_f32_e32 v46, v44, v43
	v_fma_f32 v42, -v42, v46, v45
	v_div_fmas_f32 v42, v42, v43, v46
	v_div_fixup_f32 v42, v42, v41, v40
	v_mul_f32_e32 v34, v34, v42
	v_div_scale_f32 v55, vcc, v50, v51, v50
	v_mul_f32_e32 v56, v55, v53
	v_fma_f32 v54, -v52, v56, v55
	v_fmac_f32_e32 v56, v54, v53
	v_fma_f32 v52, -v52, v56, v55
	v_div_fmas_f32 v52, v52, v53, v56
	v_div_fixup_f32 v52, v52, v51, v50
	v_mul_f32_e32 v36, v36, v52
	v_cvt_pk_bf16_f32 v209, v34, v36
	global_store_dwordx4 v[250:251], v[198:201], off offset:1024
	global_store_dwordx4 v[250:251], v[206:209], off offset:3072
	s_mov_b64 s[0:1], 0
